# wconv: 16 serialized weight loads per tile batched (2 copies); DN3: batched DNQ/DNS/DNO loads
# speedup vs baseline: 1.0241x; 1.0111x over previous
; __device__ __forceinline__ void dn3_item(const Params& p, int l, int item, unsigned char* lds) {
;     ...
;     __syncthreads();
; #pragma unroll
;     for (int e = 0; e < 4; ++e) {
;         const int id = tid + 256 * e, row = id >> 4, c4 = (id & 15) * 4;
;         *(f32x4*)(B0 + row * DLD + c4) = *(const f32x4*)(DNQ + row * 64 + c4);
;         *(f32x4*)(B1 + row * DLD + c4) = *(const f32x4*)(DNS + row * 64 + c4);
;     }
;     __syncthreads();
;     float acc[4][4];
; #pragma unroll
;     for (int rr = 0; rr < 4; ++rr) { const f32x4 o = *(const f32x4*)(DNO + (4 * ty + rr) * 64 + 4 * tx); acc[rr][0] = o.x; acc[rr][1] = o.y; acc[rr][2] = o.z; acc[rr][3] = o.w; }
.LBB0_180:
	s_lshl_b32 s0, s7, 3
	s_add_i32 s0, s40, s0
	s_add_i32 s88, s0, 0xfffff800
	s_waitcnt vmcnt(45)
	v_mov_b32_e32 v20, v179
	s_lshl_b64 s[0:1], s[88:89], 14
	s_add_u32 s4, s37, s0
	v_ashrrev_i32_e32 v19, 4, v20
	v_lshlrev_b32_e32 v0, 2, v20
	v_and_b32_e32 v18, 60, v0
	v_lshlrev_b32_e32 v2, 6, v19
	s_addc_u32 s5, s56, s1
	v_lshlrev_b32_e32 v0, 2, v18
	v_ashrrev_i32_e32 v3, 31, v2
	s_add_u32 s8, s57, s0
	s_addc_u32 s9, s68, s1
	v_lshl_add_u32 v34, v19, 8, v0
	v_add_u32_e32 v35, 0x1000, v34
	v_add_u32_e32 v21, 0x2000, v34
	v_add_u32_e32 v52, 0x3000, v34
	global_load_dwordx4 v[22:25], v34, s[4:5]
	global_load_dwordx4 v[26:29], v34, s[8:9]
	global_load_dwordx4 v[30:33], v35, s[4:5]
	global_load_dwordx4 v[36:39], v35, s[8:9]
	global_load_dwordx4 v[40:43], v21, s[4:5]
	global_load_dwordx4 v[44:47], v21, s[8:9]
	global_load_dwordx4 v[48:51], v52, s[4:5]
	global_load_dwordx4 v[238:241], v52, s[8:9]
	s_add_u32 s0, s69, s0
	s_addc_u32 s1, s70, s1
	v_lshlrev_b32_e32 v2, 8, v19
	v_lshl_add_u64 v[4:5], s[0:1], 0, v[0:1]
	v_ashrrev_i32_e32 v3, 31, v2
	v_lshl_add_u64 v[2:3], v[2:3], 2, v[4:5]
	global_load_dwordx4 v[14:17], v[2:3], off
	global_load_dwordx4 v[10:13], v[2:3], off offset:256
	global_load_dwordx4 v[6:9], v[2:3], off offset:512
	s_nop 0
	global_load_dwordx4 v[2:5], v[2:3], off offset:768
	v_mul_u32_u24_e32 v53, 0x110, v19
	v_add_u32_e32 v53, v53, v0
	s_barrier
	s_waitcnt vmcnt(11)
	ds_write_b128 v53, v[22:25]
	s_waitcnt vmcnt(10)
	ds_write_b128 v53, v[26:29] offset:17408
	s_waitcnt vmcnt(9)
	ds_write_b128 v53, v[30:33] offset:4352
	s_waitcnt vmcnt(8)
	ds_write_b128 v53, v[36:39] offset:21760
	s_waitcnt vmcnt(7)
	ds_write_b128 v53, v[40:43] offset:8704
	s_waitcnt vmcnt(6)
	ds_write_b128 v53, v[44:47] offset:26112
	s_waitcnt vmcnt(5)
	ds_write_b128 v53, v[48:51] offset:13056
	s_waitcnt vmcnt(4)
	ds_write_b128 v53, v[238:241] offset:30464
	s_movk_i32 s8, 0x110
	s_waitcnt lgkmcnt(0)
	s_barrier
	v_lshlrev_b32_e32 v0, 2, v19
	v_and_b32_e32 v19, -16, v20
	v_and_b32_e32 v20, 15, v20
	v_readlane_b32 s0, v253, 47
	v_add_u32_e32 v19, 0, v19
	s_nop 0
	v_lshl_add_u32 v20, v20, 4, s0
	s_mov_b32 s0, 0
	v_add_u32_e32 v21, s0, v19
	v_add_u32_e32 v34, s0, v20
	ds_read_b128 v[22:25], v21
	ds_read_b128 v[26:29], v34
	s_waitcnt vmcnt(0)

; __device__ __forceinline__ int tidx() { int t = threadIdx.x; asm volatile("" : "+v"(t)); return t; }
; __device__ __forceinline__ void wconv_tile(const WDesc& d, int tile, float* lds) {
;     const int tid = tidx();
;     const int nkt = d.K >> 6;
;     const int tk = tile % nkt, tn = tile / nkt;
;     {
;         const int n = (tn << 6) + (tid & 63);
;         const int sc = srccol(d.kind, n);
; #pragma unroll
;         for (int r = 0; r < 16; ++r) {
;             const int kk = (tid >> 6) + 4 * r;
;             const int k = (tk << 6) + kk;
;             float v = 0.f;
;             if (sc >= 0) v = d.W[(size_t)k * d.ldw + sc];
;             if (d.kgain) v *= d.kgain[k];
;             lds[(tid & 63) * 65 + kk] = v;
;         }
;     }
.LBB0_907:
	s_mul_i32 s28, s28, s27
	s_sub_i32 s23, s23, s28
	v_ashrrev_i32_e32 v2, 6, v8
	s_lshl_b32 s52, s23, 6
	v_add_u32_e32 v6, s52, v2
	v_cmp_lt_i32_e64 s[40:41], -1, v0
	s_waitcnt vmcnt(4)
	v_lshl_add_u64 v[4:5], v[0:1], 2, s[0:1]
	v_mov_b32_e32 v9, 0
	v_ashrrev_i32_e32 v7, 31, v6
	v_mov_b32_e32 v20, 0
	v_mov_b32_e32 v21, 0
	v_mov_b32_e32 v22, 0
	v_mov_b32_e32 v23, 0
	v_mov_b32_e32 v24, 0
	v_mov_b32_e32 v25, 0
	v_mov_b32_e32 v26, 0
	v_mov_b32_e32 v27, 0
	v_mov_b32_e32 v28, 0
	v_mov_b32_e32 v29, 0
	v_mov_b32_e32 v30, 0
	v_mov_b32_e32 v31, 0
	v_mov_b32_e32 v32, 0
	v_mov_b32_e32 v33, 0
	v_mov_b32_e32 v34, 0
	v_mov_b32_e32 v35, 0
	s_lshl_b64 s[26:27], s[82:83], 4
	s_and_saveexec_b64 s[0:1], s[40:41]
	s_cbranch_execz .Lmy_wcA_1
	v_mul_lo_u32 v0, s83, v6
	v_mul_lo_u32 v9, s82, v7
	v_mad_u64_u32 v[10:11], vcc, s82, v6, 0
	v_add3_u32 v11, v11, v9, v0
	v_lshl_add_u64 v[10:11], v[10:11], 2, v[4:5]
	global_load_dword v20, v[10:11], off
	v_lshl_add_u64 v[10:11], v[10:11], 0, s[26:27]
	global_load_dword v21, v[10:11], off
	v_lshl_add_u64 v[10:11], v[10:11], 0, s[26:27]
	global_load_dword v22, v[10:11], off
	v_lshl_add_u64 v[10:11], v[10:11], 0, s[26:27]
	global_load_dword v23, v[10:11], off
	v_lshl_add_u64 v[10:11], v[10:11], 0, s[26:27]
	global_load_dword v24, v[10:11], off
	v_lshl_add_u64 v[10:11], v[10:11], 0, s[26:27]
	global_load_dword v25, v[10:11], off
	v_lshl_add_u64 v[10:11], v[10:11], 0, s[26:27]
	global_load_dword v26, v[10:11], off
	v_lshl_add_u64 v[10:11], v[10:11], 0, s[26:27]
	global_load_dword v27, v[10:11], off
	v_lshl_add_u64 v[10:11], v[10:11], 0, s[26:27]
	global_load_dword v28, v[10:11], off
	v_lshl_add_u64 v[10:11], v[10:11], 0, s[26:27]
	global_load_dword v29, v[10:11], off
	v_lshl_add_u64 v[10:11], v[10:11], 0, s[26:27]
	global_load_dword v30, v[10:11], off
	v_lshl_add_u64 v[10:11], v[10:11], 0, s[26:27]
	global_load_dword v31, v[10:11], off
	v_lshl_add_u64 v[10:11], v[10:11], 0, s[26:27]
	global_load_dword v32, v[10:11], off
	v_lshl_add_u64 v[10:11], v[10:11], 0, s[26:27]
	global_load_dword v33, v[10:11], off
	v_lshl_add_u64 v[10:11], v[10:11], 0, s[26:27]
	global_load_dword v34, v[10:11], off
	v_lshl_add_u64 v[10:11], v[10:11], 0, s[26:27]
	global_load_dword v35, v[10:11], off
.Lmy_wcA_1:
	s_or_b64 exec, exec, s[0:1]
	s_cmp_lg_u64 s[90:91], 0
	s_cselect_b64 s[54:55], -1, 0
	s_ashr_i32 s53, s52, 31
	s_cmp_eq_u64 s[90:91], 0
	s_cbranch_scc1 .Lmy_wcB_1
	v_lshl_add_u64 v[10:11], v[6:7], 2, s[90:91]
	global_load_dword v36, v[10:11], off
	global_load_dword v37, v[10:11], off offset:16
	global_load_dword v38, v[10:11], off offset:32
	global_load_dword v39, v[10:11], off offset:48
	global_load_dword v40, v[10:11], off offset:64
	global_load_dword v41, v[10:11], off offset:80
	global_load_dword v42, v[10:11], off offset:96
	global_load_dword v43, v[10:11], off offset:112
	global_load_dword v44, v[10:11], off offset:128
	global_load_dword v45, v[10:11], off offset:144
	global_load_dword v46, v[10:11], off offset:160
	global_load_dword v47, v[10:11], off offset:176
	global_load_dword v48, v[10:11], off offset:192
	global_load_dword v49, v[10:11], off offset:208
	global_load_dword v50, v[10:11], off offset:224
	global_load_dword v51, v[10:11], off offset:240
	s_waitcnt vmcnt(0)
	v_mul_f32_e32 v20, v20, v36
	v_mul_f32_e32 v21, v21, v37
	v_mul_f32_e32 v22, v22, v38
	v_mul_f32_e32 v23, v23, v39
	v_mul_f32_e32 v24, v24, v40
	v_mul_f32_e32 v25, v25, v41
	v_mul_f32_e32 v26, v26, v42
	v_mul_f32_e32 v27, v27, v43
	v_mul_f32_e32 v28, v28, v44
	v_mul_f32_e32 v29, v29, v45
	v_mul_f32_e32 v30, v30, v46
	v_mul_f32_e32 v31, v31, v47
	v_mul_f32_e32 v32, v32, v48
	v_mul_f32_e32 v33, v33, v49
	v_mul_f32_e32 v34, v34, v50
	v_mul_f32_e32 v35, v35, v51
.Lmy_wcB_1:
	v_mul_u32_u24_e32 v0, 0x104, v3
	v_lshlrev_b32_e32 v3, 2, v2
	v_add3_u32 v0, 0, v0, v3
	s_waitcnt vmcnt(0)
	ds_write_b32 v0, v20
	ds_write_b32 v0, v21 offset:16
	ds_write_b32 v0, v22 offset:32
	ds_write_b32 v0, v23 offset:48
	ds_write_b32 v0, v24 offset:64
	ds_write_b32 v0, v25 offset:80
	ds_write_b32 v0, v26 offset:96
	ds_write_b32 v0, v27 offset:112
	ds_write_b32 v0, v28 offset:128
	ds_write_b32 v0, v29 offset:144
	ds_write_b32 v0, v30 offset:160
	ds_write_b32 v0, v31 offset:176
	ds_write_b32 v0, v32 offset:192
	ds_write_b32 v0, v33 offset:208
	ds_write_b32 v0, v34 offset:224
	v_mov_b32_e32 v2, v35
	s_branch .LBB0_798

; __device__ __forceinline__ int tidx() { int t = threadIdx.x; asm volatile("" : "+v"(t)); return t; }
; __device__ __forceinline__ void wconv_tile(const WDesc& d, int tile, float* lds) {
;     const int tid = tidx();
;     const int nkt = d.K >> 6;
;     const int tk = tile % nkt, tn = tile / nkt;
;     {
;         const int n = (tn << 6) + (tid & 63);
;         const int sc = srccol(d.kind, n);
; #pragma unroll
;         for (int r = 0; r < 16; ++r) {
;             const int kk = (tid >> 6) + 4 * r;
;             const int k = (tk << 6) + kk;
;             float v = 0.f;
;             if (sc >= 0) v = d.W[(size_t)k * d.ldw + sc];
;             if (d.kgain) v *= d.kgain[k];
;             lds[(tid & 63) * 65 + kk] = v;
;         }
;     }
.LBB0_1103:
	s_mul_i32 s69, s69, s68
	s_sub_i32 s40, s56, s69
	v_ashrrev_i32_e32 v2, 6, v8
	s_lshl_b32 s44, s40, 6
	v_add_u32_e32 v6, s44, v2
	v_cmp_lt_i32_e64 s[40:41], -1, v0
	v_lshl_add_u64 v[4:5], v[0:1], 2, s[0:1]
	v_mov_b32_e32 v9, 0
	v_ashrrev_i32_e32 v7, 31, v6
	v_mov_b32_e32 v20, 0
	v_mov_b32_e32 v21, 0
	v_mov_b32_e32 v22, 0
	v_mov_b32_e32 v23, 0
	v_mov_b32_e32 v24, 0
	v_mov_b32_e32 v25, 0
	v_mov_b32_e32 v26, 0
	v_mov_b32_e32 v27, 0
	v_mov_b32_e32 v28, 0
	v_mov_b32_e32 v29, 0
	v_mov_b32_e32 v30, 0
	v_mov_b32_e32 v31, 0
	v_mov_b32_e32 v32, 0
	v_mov_b32_e32 v33, 0
	v_mov_b32_e32 v34, 0
	v_mov_b32_e32 v35, 0
	s_lshl_b64 s[46:47], s[38:39], 4
	s_and_saveexec_b64 s[0:1], s[40:41]
	s_cbranch_execz .Lmy_wcA_0
	v_mul_lo_u32 v0, s39, v6
	v_mul_lo_u32 v9, s38, v7
	v_mad_u64_u32 v[10:11], vcc, s38, v6, 0
	v_add3_u32 v11, v11, v9, v0
	v_lshl_add_u64 v[10:11], v[10:11], 2, v[4:5]
	global_load_dword v20, v[10:11], off
	v_lshl_add_u64 v[10:11], v[10:11], 0, s[46:47]
	global_load_dword v21, v[10:11], off
	v_lshl_add_u64 v[10:11], v[10:11], 0, s[46:47]
	global_load_dword v22, v[10:11], off
	v_lshl_add_u64 v[10:11], v[10:11], 0, s[46:47]
	global_load_dword v23, v[10:11], off
	v_lshl_add_u64 v[10:11], v[10:11], 0, s[46:47]
	global_load_dword v24, v[10:11], off
	v_lshl_add_u64 v[10:11], v[10:11], 0, s[46:47]
	global_load_dword v25, v[10:11], off
	v_lshl_add_u64 v[10:11], v[10:11], 0, s[46:47]
	global_load_dword v26, v[10:11], off
	v_lshl_add_u64 v[10:11], v[10:11], 0, s[46:47]
	global_load_dword v27, v[10:11], off
	v_lshl_add_u64 v[10:11], v[10:11], 0, s[46:47]
	global_load_dword v28, v[10:11], off
	v_lshl_add_u64 v[10:11], v[10:11], 0, s[46:47]
	global_load_dword v29, v[10:11], off
	v_lshl_add_u64 v[10:11], v[10:11], 0, s[46:47]
	global_load_dword v30, v[10:11], off
	v_lshl_add_u64 v[10:11], v[10:11], 0, s[46:47]
	global_load_dword v31, v[10:11], off
	v_lshl_add_u64 v[10:11], v[10:11], 0, s[46:47]
	global_load_dword v32, v[10:11], off
	v_lshl_add_u64 v[10:11], v[10:11], 0, s[46:47]
	global_load_dword v33, v[10:11], off
	v_lshl_add_u64 v[10:11], v[10:11], 0, s[46:47]
	global_load_dword v34, v[10:11], off
	v_lshl_add_u64 v[10:11], v[10:11], 0, s[46:47]
	global_load_dword v35, v[10:11], off
.Lmy_wcA_0:
	s_or_b64 exec, exec, s[0:1]
	s_movk_i32 s56, 0x7fff
	s_cmp_lg_u64 s[42:43], 0
	s_cselect_b64 s[46:47], -1, 0
	s_ashr_i32 s45, s44, 31
	s_cmp_eq_u64 s[42:43], 0
	s_cbranch_scc1 .Lmy_wcB_0
	v_lshl_add_u64 v[10:11], v[6:7], 2, s[42:43]
	global_load_dword v36, v[10:11], off
	global_load_dword v37, v[10:11], off offset:16
	global_load_dword v38, v[10:11], off offset:32
	global_load_dword v39, v[10:11], off offset:48
	global_load_dword v40, v[10:11], off offset:64
	global_load_dword v41, v[10:11], off offset:80
	global_load_dword v42, v[10:11], off offset:96
	global_load_dword v43, v[10:11], off offset:112
	global_load_dword v44, v[10:11], off offset:128
	global_load_dword v45, v[10:11], off offset:144
	global_load_dword v46, v[10:11], off offset:160
	global_load_dword v47, v[10:11], off offset:176
	global_load_dword v48, v[10:11], off offset:192
	global_load_dword v49, v[10:11], off offset:208
	global_load_dword v50, v[10:11], off offset:224
	global_load_dword v51, v[10:11], off offset:240
	s_waitcnt vmcnt(0)
	v_mul_f32_e32 v20, v20, v36
	v_mul_f32_e32 v21, v21, v37
	v_mul_f32_e32 v22, v22, v38
	v_mul_f32_e32 v23, v23, v39
	v_mul_f32_e32 v24, v24, v40
	v_mul_f32_e32 v25, v25, v41
	v_mul_f32_e32 v26, v26, v42
	v_mul_f32_e32 v27, v27, v43
	v_mul_f32_e32 v28, v28, v44
	v_mul_f32_e32 v29, v29, v45
	v_mul_f32_e32 v30, v30, v46
	v_mul_f32_e32 v31, v31, v47
	v_mul_f32_e32 v32, v32, v48
	v_mul_f32_e32 v33, v33, v49
	v_mul_f32_e32 v34, v34, v50
	v_mul_f32_e32 v35, v35, v51
